# stack5 + P7 per-block fb-table loads de-serialized
# speedup vs baseline: 1.0120x; 1.0010x over previous
.LBB0_1107:
	s_add_i32 s14, s76, 0xff
	s_ashr_i32 s15, s14, 31
	s_lshr_b32 s15, s15, 26
	s_add_i32 s14, s14, s15
	s_ashr_i32 s14, s14, 6
	s_add_i32 s15, s14, 1
	s_lshr_b32 s25, s91, 6
	s_cmp_lt_i32 s14, s25
	s_cselect_b32 s14, s15, s25
	s_lshl_b32 s53, s14, 6
	v_cndmask_b32_e64 v0, 0, 1, s[0:1]
	v_cmp_ne_u32_e64 s[42:43], 1, v0
	s_nop 1
	s_and_b64 vcc, exec, s[42:43]
	s_cbranch_vccnz .Lp7fb_zero
	v_ashrrev_i32_e32 v165, 31, v164
	v_lshl_add_u64 v[4:5], v[164:165], 2, s[44:45]
	s_mov_b64 s[0:1], 0x1000
	v_lshl_add_u64 v[0:1], v[4:5], 0, s[0:1]
	global_load_dword v163, v[4:5], off
	global_load_dword v187, v[4:5], off offset:2048
	global_load_dword v160, v[0:1], off
	global_load_dword v179, v[0:1], off offset:2048
	s_waitcnt vmcnt(0)
	v_sub_f32_e32 v163, v2, v163
	v_sub_f32_e32 v187, v2, v187
	v_sub_f32_e32 v160, v2, v160
	v_sub_f32_e32 v179, v2, v179
	v_mul_f32_e32 v163, 0x413504f3, v163
	v_mul_f32_e32 v187, 0x413504f3, v187
	v_mul_f32_e32 v160, 0x413504f3, v160
	v_mul_f32_e32 v179, 0x413504f3, v179
	s_branch .Lp7fb_store
.Lp7fb_zero:
	v_mov_b32_e32 v163, 0
	v_mov_b32_e32 v187, 0
	v_mov_b32_e32 v160, 0
	v_mov_b32_e32 v179, 0
.Lp7fb_store:
	v_lshl_add_u32 v1, v164, 2, 0
	v_add_u32_e32 v1, 0x10800, v1
	ds_write_b32 v1, v163
	ds_write_b32 v1, v187 offset:2048
	ds_write_b32 v1, v160 offset:4096
	ds_write_b32 v1, v179 offset:6144
.LBB0_1127:
	v_ashrrev_i32_e32 v163, 4, v164
	v_add_u32_e32 v187, 32, v163
	v_and_b32_e32 v1, 0xfffff0, v163
	s_waitcnt vmcnt(0)
	v_lshlrev_b32_e32 v2, 1, v163
	v_and_b32_e32 v4, 0xfffff0, v187
	v_lshlrev_b32_e32 v5, 1, v187
	v_lshlrev_b32_e32 v0, 3, v164
	v_and_or_b32 v1, v2, 8, v1
	v_and_or_b32 v4, v5, 8, v4
	v_and_b32_e32 v179, 0x78, v0
	v_lshrrev_b32_e32 v2, 1, v163
	v_lshrrev_b32_e32 v1, 1, v1
	v_bfe_u32 v0, v0, 5, 2
	v_and_b32_e32 v3, 3, v163
	v_lshrrev_b32_e32 v4, 1, v4
	v_or_b32_e32 v1, v1, v0
	v_and_or_b32 v2, v2, 4, v3
	v_lshlrev_b32_e32 v160, 1, v179
	v_or_b32_e32 v0, v4, v0
	v_lshlrev_b32_e32 v1, 9, v1
	v_lshlrev_b32_e32 v2, 6, v2
	v_and_b32_e32 v3, 48, v160
	v_lshlrev_b32_e32 v0, 9, v0
	v_or3_b32 v1, v1, v2, v3
	v_or3_b32 v0, v0, v2, v3
	s_sub_i32 s83, s14, s90
	v_add_u32_e32 v199, 0, v1
	v_add_u32_e32 v200, 0, v0
	s_waitcnt lgkmcnt(0)
	s_barrier
	ds_write_b128 v199, v[96:99]
	ds_write_b128 v200, v[100:103]
	s_cmp_gt_i32 s83, 1
	s_cselect_b64 s[14:15], -1, 0
	s_lshl_b32 s25, s90, 6
	s_cmp_lt_i32 s83, 2
	s_cbranch_scc1 .LBB0_1129
	s_add_i32 s0, s25, 64
	v_add_u32_e32 v0, s0, v163
	v_ashrrev_i32_e32 v1, 31, v0
	v_add_u32_e32 v4, s0, v187
	v_lshlrev_b64 v[0:1], 8, v[0:1]
	v_ashrrev_i32_e32 v5, 31, v4
	v_lshl_add_u64 v[2:3], s[38:39], 0, v[0:1]
	v_lshlrev_b64 v[4:5], 8, v[4:5]
	v_lshl_add_u64 v[2:3], v[2:3], 0, v[160:161]
	v_lshl_add_u64 v[6:7], s[38:39], 0, v[4:5]
	v_lshl_add_u64 v[0:1], s[4:5], 0, v[0:1]
	v_lshl_add_u64 v[6:7], v[6:7], 0, v[160:161]
	global_load_dwordx4 v[96:99], v[2:3], off
	global_load_dwordx4 v[100:103], v[6:7], off
	v_lshl_add_u64 v[0:1], v[0:1], 0, v[160:161]
	v_lshl_add_u64 v[2:3], s[4:5], 0, v[4:5]
	v_lshl_add_u64 v[2:3], v[2:3], 0, v[160:161]
	global_load_dwordx4 v[104:107], v[0:1], off
	global_load_dwordx4 v[108:111], v[2:3], off
